# prologue in-proj weight transpose: 32 loads kept in flight instead of 32 serialized round trips; last-layer norm pass loads batched
# speedup vs baseline: 1.0401x; 1.0128x over previous
.LBB0_19:
	s_andn2_saveexec_b64 s[18:19], s[0:1]
	s_cbranch_execz .LBB0_2
	v_lshlrev_b64 v[42:43], 2, v[4:5]
	v_add_u32_e32 v4, v52, v18
	s_load_dwordx4 s[0:3], s[8:9], 0x10
	v_mul_hi_i32_i24_e32 v27, 0x9880, v4
	v_mul_i32_i24_e32 v26, 0x9880, v4
	v_add_u32_e32 v4, v53, v18
	v_mul_hi_i32_i24_e32 v29, 0x9880, v4
	v_mul_i32_i24_e32 v28, 0x9880, v4
	v_add_u32_e32 v4, v54, v18
	v_mul_hi_i32_i24_e32 v31, 0x9880, v4
	v_mul_i32_i24_e32 v30, 0x9880, v4
	v_add_u32_e32 v4, v55, v18
	v_mul_hi_i32_i24_e32 v33, 0x9880, v4
	v_mul_i32_i24_e32 v32, 0x9880, v4
	v_add_u32_e32 v4, v56, v18
	v_add_u32_e32 v66, v10, v18
	v_ashrrev_i32_e32 v19, 31, v18
	v_add_u32_e32 v13, v51, v18
	v_mul_hi_i32_i24_e32 v35, 0x9880, v4
	v_mul_i32_i24_e32 v34, 0x9880, v4
	v_add_u32_e32 v4, v57, v18
	v_ashrrev_i32_e32 v67, 31, v66
	v_lshl_add_u64 v[24:25], v[10:11], 0, v[18:19]
	v_mul_hi_i32_i24_e32 v21, 0x9880, v13
	v_mul_i32_i24_e32 v20, 0x9880, v13
	v_mul_hi_i32_i24_e32 v37, 0x9880, v4
	v_mul_i32_i24_e32 v36, 0x9880, v4
	s_waitcnt lgkmcnt(0)
	v_lshl_add_u64 v[38:39], v[66:67], 2, s[0:1]
	v_mul_hi_i32_i24_e32 v67, 0x9880, v66
	v_mul_i32_i24_e32 v66, 0x9880, v66
	v_lshlrev_b32_e32 v22, 10, v16
	s_cmp_lg_u64 s[0:1], 0
	v_lshl_add_u64 v[40:41], s[2:3], 0, v[6:7]
	v_mad_i64_i32 v[20:21], s[2:3], v16, s33, v[20:21]
	v_lshl_add_u64 v[24:25], v[24:25], 2, s[0:1]
	v_mad_i64_i32 v[26:27], s[2:3], v16, s33, v[26:27]
	v_mad_i64_i32 v[28:29], s[2:3], v16, s33, v[28:29]
	v_mad_i64_i32 v[30:31], s[2:3], v16, s33, v[30:31]
	v_mad_i64_i32 v[32:33], s[2:3], v16, s33, v[32:33]
	v_mad_i64_i32 v[34:35], s[2:3], v16, s33, v[34:35]
	v_mad_i64_i32 v[36:37], s[2:3], v16, s33, v[36:37]
	v_mad_i64_i32 v[66:67], s[0:1], v16, s33, v[66:67]
	v_ashrrev_i32_e32 v23, 31, v22
	v_lshl_add_u64 v[20:21], v[20:21], 0, v[42:43]
	v_lshl_add_u64 v[26:27], v[26:27], 0, v[42:43]
	v_lshl_add_u64 v[28:29], v[28:29], 0, v[42:43]
	v_lshl_add_u64 v[30:31], v[30:31], 0, v[42:43]
	v_lshl_add_u64 v[32:33], v[32:33], 0, v[42:43]
	v_lshl_add_u64 v[34:35], v[34:35], 0, v[42:43]
	v_lshl_add_u64 v[36:37], v[36:37], 0, v[42:43]
	v_lshl_add_u64 v[42:43], v[66:67], 0, v[42:43]
	s_mov_b64 s[20:21], 0
	s_cselect_b64 s[22:23], -1, 0
	v_lshl_add_u64 v[20:21], v[40:41], 0, v[20:21]
	v_lshlrev_b64 v[22:23], 2, v[22:23]
	v_lshl_add_u64 v[26:27], v[40:41], 0, v[26:27]
	v_lshl_add_u64 v[28:29], v[40:41], 0, v[28:29]
	v_lshl_add_u64 v[30:31], v[40:41], 0, v[30:31]
	v_lshl_add_u64 v[32:33], v[40:41], 0, v[32:33]
	v_lshl_add_u64 v[34:35], v[40:41], 0, v[34:35]
	v_lshl_add_u64 v[36:37], v[40:41], 0, v[36:37]
	v_lshl_add_u64 v[40:41], v[40:41], 0, v[42:43]
	v_mov_b32_e32 v4, v50
	s_andn2_b64 vcc, exec, s[22:23]
	s_cbranch_vccnz .LBB0_22
	v_lshl_add_u64 v[42:43], v[40:41], 0, s[20:21]
	global_load_dword v90, v[42:43], off
	v_lshl_add_u64 v[42:43], v[36:37], 0, s[20:21]
	global_load_dword v91, v[42:43], off
	v_lshl_add_u64 v[42:43], v[34:35], 0, s[20:21]
	global_load_dword v92, v[42:43], off
	v_lshl_add_u64 v[42:43], v[32:33], 0, s[20:21]
	global_load_dword v93, v[42:43], off
	v_lshl_add_u64 v[42:43], v[30:31], 0, s[20:21]
	global_load_dword v94, v[42:43], off
	v_lshl_add_u64 v[42:43], v[28:29], 0, s[20:21]
	global_load_dword v95, v[42:43], off
	v_lshl_add_u64 v[42:43], v[26:27], 0, s[20:21]
	global_load_dword v96, v[42:43], off
	v_lshl_add_u64 v[42:43], v[20:21], 0, s[20:21]
	global_load_dword v97, v[42:43], off
	v_lshl_add_u64 v[66:67], v[38:39], 0, v[22:23]
	global_load_dword v106, v[66:67], off
	v_lshl_add_u64 v[66:67], v[24:25], 0, v[22:23]
	global_load_dword v107, v[66:67], off offset:8
	global_load_dword v108, v[66:67], off offset:16
	global_load_dword v109, v[66:67], off offset:24
	global_load_dword v110, v[66:67], off offset:32
	global_load_dword v111, v[66:67], off offset:40
	global_load_dword v112, v[66:67], off offset:48
	global_load_dword v113, v[66:67], off offset:56
	s_add_u32 s20, s20, 0x98800
	s_addc_u32 s21, s21, 0
	v_lshl_add_u64 v[24:25], v[24:25], 0, 64
	v_lshl_add_u64 v[38:39], v[38:39], 0, 64
	v_lshl_add_u64 v[42:43], v[40:41], 0, s[20:21]
	global_load_dword v98, v[42:43], off
	v_lshl_add_u64 v[42:43], v[36:37], 0, s[20:21]
	global_load_dword v99, v[42:43], off
	v_lshl_add_u64 v[42:43], v[34:35], 0, s[20:21]
	global_load_dword v100, v[42:43], off
	v_lshl_add_u64 v[42:43], v[32:33], 0, s[20:21]
	global_load_dword v101, v[42:43], off
	v_lshl_add_u64 v[42:43], v[30:31], 0, s[20:21]
	global_load_dword v102, v[42:43], off
	v_lshl_add_u64 v[42:43], v[28:29], 0, s[20:21]
	global_load_dword v103, v[42:43], off
	v_lshl_add_u64 v[42:43], v[26:27], 0, s[20:21]
	global_load_dword v104, v[42:43], off
	v_lshl_add_u64 v[42:43], v[20:21], 0, s[20:21]
	global_load_dword v105, v[42:43], off
	v_lshl_add_u64 v[66:67], v[38:39], 0, v[22:23]
	global_load_dword v114, v[66:67], off
	v_lshl_add_u64 v[66:67], v[24:25], 0, v[22:23]
	global_load_dword v115, v[66:67], off offset:8
	global_load_dword v116, v[66:67], off offset:16
	global_load_dword v117, v[66:67], off offset:24
	global_load_dword v118, v[66:67], off offset:32
	global_load_dword v119, v[66:67], off offset:40
	global_load_dword v120, v[66:67], off offset:48
	global_load_dword v121, v[66:67], off offset:56
	s_add_u32 s20, s20, 0x98800
	s_addc_u32 s21, s21, 0
	v_lshl_add_u64 v[24:25], v[24:25], 0, 64
	v_lshl_add_u64 v[38:39], v[38:39], 0, 64
	s_waitcnt vmcnt(16)
	v_mul_f32_e32 v90, v90, v106
	v_mul_f32_e32 v91, v91, v107
	v_mul_f32_e32 v92, v92, v108
	v_mul_f32_e32 v93, v93, v109
	v_mul_f32_e32 v94, v94, v110
	v_mul_f32_e32 v95, v95, v111
	v_mul_f32_e32 v96, v96, v112
	v_mul_f32_e32 v97, v97, v113
	ds_write_b32 v4, v90
	ds_write_b32 v4, v91 offset:264
	ds_write_b32 v4, v92 offset:528
	ds_write_b32 v4, v93 offset:792
	ds_write_b32 v4, v94 offset:1056
	ds_write_b32 v4, v95 offset:1320
	ds_write_b32 v4, v96 offset:1584
	ds_write_b32 v4, v97 offset:1848
	v_add_u32_e32 v4, 0x840, v4
	v_lshl_add_u64 v[42:43], v[40:41], 0, s[20:21]
	global_load_dword v90, v[42:43], off
	v_lshl_add_u64 v[42:43], v[36:37], 0, s[20:21]
	global_load_dword v91, v[42:43], off
	v_lshl_add_u64 v[42:43], v[34:35], 0, s[20:21]
	global_load_dword v92, v[42:43], off
	v_lshl_add_u64 v[42:43], v[32:33], 0, s[20:21]
	global_load_dword v93, v[42:43], off
	v_lshl_add_u64 v[42:43], v[30:31], 0, s[20:21]
	global_load_dword v94, v[42:43], off
	v_lshl_add_u64 v[42:43], v[28:29], 0, s[20:21]
	global_load_dword v95, v[42:43], off
	v_lshl_add_u64 v[42:43], v[26:27], 0, s[20:21]
	global_load_dword v96, v[42:43], off
	v_lshl_add_u64 v[42:43], v[20:21], 0, s[20:21]
	global_load_dword v97, v[42:43], off
	v_lshl_add_u64 v[66:67], v[38:39], 0, v[22:23]
	global_load_dword v106, v[66:67], off
	v_lshl_add_u64 v[66:67], v[24:25], 0, v[22:23]
	global_load_dword v107, v[66:67], off offset:8
	global_load_dword v108, v[66:67], off offset:16
	global_load_dword v109, v[66:67], off offset:24
	global_load_dword v110, v[66:67], off offset:32
	global_load_dword v111, v[66:67], off offset:40
	global_load_dword v112, v[66:67], off offset:48
	global_load_dword v113, v[66:67], off offset:56
	s_add_u32 s20, s20, 0x98800
	s_addc_u32 s21, s21, 0
	v_lshl_add_u64 v[24:25], v[24:25], 0, 64
	v_lshl_add_u64 v[38:39], v[38:39], 0, 64
	s_waitcnt vmcnt(16)
	v_mul_f32_e32 v98, v98, v114
	v_mul_f32_e32 v99, v99, v115
	v_mul_f32_e32 v100, v100, v116
	v_mul_f32_e32 v101, v101, v117
	v_mul_f32_e32 v102, v102, v118
	v_mul_f32_e32 v103, v103, v119
	v_mul_f32_e32 v104, v104, v120
	v_mul_f32_e32 v105, v105, v121
	ds_write_b32 v4, v98
	ds_write_b32 v4, v99 offset:264
	ds_write_b32 v4, v100 offset:528
	ds_write_b32 v4, v101 offset:792
	ds_write_b32 v4, v102 offset:1056
	ds_write_b32 v4, v103 offset:1320
	ds_write_b32 v4, v104 offset:1584
	ds_write_b32 v4, v105 offset:1848
	v_add_u32_e32 v4, 0x840, v4
	v_lshl_add_u64 v[42:43], v[40:41], 0, s[20:21]
	global_load_dword v98, v[42:43], off
	v_lshl_add_u64 v[42:43], v[36:37], 0, s[20:21]
	global_load_dword v99, v[42:43], off
	v_lshl_add_u64 v[42:43], v[34:35], 0, s[20:21]
	global_load_dword v100, v[42:43], off
	v_lshl_add_u64 v[42:43], v[32:33], 0, s[20:21]
	global_load_dword v101, v[42:43], off
	v_lshl_add_u64 v[42:43], v[30:31], 0, s[20:21]
	global_load_dword v102, v[42:43], off
	v_lshl_add_u64 v[42:43], v[28:29], 0, s[20:21]
	global_load_dword v103, v[42:43], off
	v_lshl_add_u64 v[42:43], v[26:27], 0, s[20:21]
	global_load_dword v104, v[42:43], off
	v_lshl_add_u64 v[42:43], v[20:21], 0, s[20:21]
	global_load_dword v105, v[42:43], off
	v_lshl_add_u64 v[66:67], v[38:39], 0, v[22:23]
	global_load_dword v114, v[66:67], off
	v_lshl_add_u64 v[66:67], v[24:25], 0, v[22:23]
	global_load_dword v115, v[66:67], off offset:8
	global_load_dword v116, v[66:67], off offset:16
	global_load_dword v117, v[66:67], off offset:24
	global_load_dword v118, v[66:67], off offset:32
	global_load_dword v119, v[66:67], off offset:40
	global_load_dword v120, v[66:67], off offset:48
	global_load_dword v121, v[66:67], off offset:56
	s_add_u32 s20, s20, 0x98800
	s_addc_u32 s21, s21, 0
	v_lshl_add_u64 v[24:25], v[24:25], 0, 64
	v_lshl_add_u64 v[38:39], v[38:39], 0, 64
	s_waitcnt vmcnt(16)
	v_mul_f32_e32 v90, v90, v106
	v_mul_f32_e32 v91, v91, v107
	v_mul_f32_e32 v92, v92, v108
	v_mul_f32_e32 v93, v93, v109
	v_mul_f32_e32 v94, v94, v110
	v_mul_f32_e32 v95, v95, v111
	v_mul_f32_e32 v96, v96, v112
	v_mul_f32_e32 v97, v97, v113
	ds_write_b32 v4, v90
	ds_write_b32 v4, v91 offset:264
	ds_write_b32 v4, v92 offset:528
	ds_write_b32 v4, v93 offset:792
	ds_write_b32 v4, v94 offset:1056
	ds_write_b32 v4, v95 offset:1320
	ds_write_b32 v4, v96 offset:1584
	ds_write_b32 v4, v97 offset:1848
	v_add_u32_e32 v4, 0x840, v4
	s_waitcnt vmcnt(0)
	v_mul_f32_e32 v98, v98, v114
	v_mul_f32_e32 v99, v99, v115
	v_mul_f32_e32 v100, v100, v116
	v_mul_f32_e32 v101, v101, v117
	v_mul_f32_e32 v102, v102, v118
	v_mul_f32_e32 v103, v103, v119
	v_mul_f32_e32 v104, v104, v120
	v_mul_f32_e32 v105, v105, v121
	ds_write_b32 v4, v98
	ds_write_b32 v4, v99 offset:264
	ds_write_b32 v4, v100 offset:528
	ds_write_b32 v4, v101 offset:792
	ds_write_b32 v4, v102 offset:1056
	ds_write_b32 v4, v103 offset:1320
	ds_write_b32 v4, v104 offset:1584
	ds_write_b32 v4, v105 offset:1848
	v_add_u32_e32 v4, 0x840, v4
	s_branch .LBB0_2

.LBB0_1137:
	global_load_dwordx4 v[0:3], v[22:23], off offset:-3072
	global_load_dwordx4 v[4:7], v[22:23], off offset:-2048
	global_load_dwordx4 v[8:11], v[22:23], off offset:-1024
	global_load_dwordx4 v[12:15], v[22:23], off
	s_waitcnt vmcnt(3)
	v_mul_f32_e32 v30, v1, v1
	v_mul_f32_e32 v31, v3, v3
	v_fmac_f32_e32 v30, v0, v0
	v_fmac_f32_e32 v31, v2, v2
	v_add_f32_e32 v17, v30, v31
	s_waitcnt vmcnt(2)
	v_mul_f32_e32 v30, v5, v5
	v_mul_f32_e32 v31, v7, v7
	v_fmac_f32_e32 v30, v4, v4
	v_fmac_f32_e32 v31, v6, v6
	v_add_f32_e32 v30, v30, v31
	v_add_f32_e32 v17, v17, v30
	s_waitcnt vmcnt(1)
	v_mul_f32_e32 v30, v9, v9
	v_mul_f32_e32 v31, v11, v11
	v_fmac_f32_e32 v30, v8, v8
	v_fmac_f32_e32 v31, v10, v10
	v_add_f32_e32 v30, v30, v31
	v_add_f32_e32 v17, v17, v30
	s_waitcnt vmcnt(0)
	v_mul_f32_e32 v30, v13, v13
	v_mul_f32_e32 v31, v15, v15
	v_fmac_f32_e32 v30, v12, v12
	v_fmac_f32_e32 v31, v14, v14
	v_add_f32_e32 v30, v30, v31
	v_add_f32_e32 v17, v17, v30
	ds_bpermute_b32 v30, v24, v17
	s_waitcnt lgkmcnt(0)
	v_add_f32_e32 v17, v17, v30
	ds_bpermute_b32 v30, v25, v17
	s_waitcnt lgkmcnt(0)
	v_add_f32_e32 v17, v17, v30
	ds_bpermute_b32 v30, v26, v17
	s_waitcnt lgkmcnt(0)
	v_add_f32_e32 v17, v17, v30
	ds_bpermute_b32 v30, v27, v17
	s_waitcnt lgkmcnt(0)
	v_add_f32_e32 v17, v17, v30
	ds_bpermute_b32 v30, v28, v17
	s_waitcnt lgkmcnt(0)
	v_add_f32_e32 v17, v17, v30
	ds_bpermute_b32 v30, v29, v17
	s_and_saveexec_b64 s[10:11], s[0:1]
	s_cbranch_execz .LBB0_1136
	s_waitcnt lgkmcnt(0)
	v_add_f32_e32 v17, v17, v30
	v_cndmask_b32_e64 v17, 0, v17, s[2:3]
	v_lshl_add_u64 v[30:31], s[6:7], 0, v[18:19]
	global_store_dword v[30:31], v17, off
	s_branch .LBB0_1136
